# GEMM epilogue waits counted: vmcnt(16)/vmcnt(8) instead of vmcnt(0) before next-unit row-stat use (no store drain)
# speedup vs baseline: 1.0266x; 1.0055x over previous
; DI unsigned pack2(float lo, float hi) { f32x2_t v = {lo, hi}; return __builtin_bit_cast(unsigned, __builtin_convertvector(v, bf16x2_t)); }
; #define PG8_LAS __attribute__((address_space(3)))
;   DI void operator()(const f32x4 (&acc)[2][2][4][2], const Unit& u, int wr, int wc, int fr, int fq, const PG8_LAS float* rt) const {
;     const int row0 = u.pm * BM + wr * 64 + fr, col0 = u.pn * BM + wc * 32 + 8 * fq;
; #pragma unroll
;     for (int ai = 0; ai < 2; ++ai)
; #pragma unroll
;       for (int m = 0; m < 4; ++m) { bf16_t* rowp = O + (size_t)(row0 + ai * HALF + m * 16) * ldc + col0; const float r = rt[ai * HALF + wr * 64 + m * 16 + fr];
; #pragma unroll
;         for (int bj = 0; bj < 2; ++bj) { const f32x4 v0 = acc[ai][bj][m][0] * r, v1 = acc[ai][bj][m][1] * r;
;           u32x4 w; w.x = pack2(v0[0], v0[1]); w.y = pack2(v0[2], v0[3]); w.z = pack2(v1[0], v1[1]); w.w = pack2(v1[2], v1[3]);
;           *(u32x4*)(rowp + bj * HALF) = w; } }
.LBB0_140:
	s_lshl_b32 s1, s53, 10
	s_and_b32 s1, s1, 0x400
	v_add_u32_e32 v182, s1, v155
	ds_read2_b32 v[176:177], v182 offset1:16
	v_lshl_or_b32 v148, s58, 8, v156
	v_lshl_add_u32 v175, s59, 8, v153
	v_ashrrev_i32_e32 v149, 31, v148
	v_mov_b64_e32 v[146:147], s[66:67]
	s_movk_i32 s1, 0xc00
	v_mad_i64_i32 v[178:179], s[22:23], v175, s1, v[146:147]
	v_lshlrev_b64 v[148:149], 1, v[148:149]
	s_waitcnt lgkmcnt(0)
	v_pk_mul_f32 v[128:129], v[128:129], v[176:177] op_sel_hi:[1,0]
	v_pk_mul_f32 v[126:127], v[126:127], v[176:177] op_sel_hi:[1,0]
	v_pk_mul_f32 v[180:181], v[124:125], v[176:177] op_sel_hi:[1,0]
	v_pk_mul_f32 v[124:125], v[122:123], v[176:177] op_sel_hi:[1,0]
	v_lshl_add_u64 v[178:179], v[178:179], 0, v[148:149]
	v_cvt_pk_bf16_f32 v122, v126, v127
	v_cvt_pk_bf16_f32 v123, v128, v129
	v_cvt_pk_bf16_f32 v124, v124, v125
	v_cvt_pk_bf16_f32 v125, v180, v181
	global_store_dwordx4 v[178:179], v[122:125], off
	v_pk_mul_f32 v[116:117], v[116:117], v[176:177] op_sel_hi:[1,0]
	v_pk_mul_f32 v[114:115], v[114:115], v[176:177] op_sel_hi:[1,0]
	v_pk_mul_f32 v[122:123], v[108:109], v[176:177] op_sel_hi:[1,0]
	v_pk_mul_f32 v[108:109], v[106:107], v[176:177] op_sel_hi:[1,0]
	v_cvt_pk_bf16_f32 v106, v114, v115
	v_cvt_pk_bf16_f32 v107, v116, v117
	v_cvt_pk_bf16_f32 v108, v108, v109
	v_cvt_pk_bf16_f32 v109, v122, v123
	global_store_dwordx4 v[178:179], v[106:109], off offset:256
	v_mov_b32_e32 v116, v177
	v_pk_mul_f32 v[112:113], v[112:113], v[116:117] op_sel_hi:[1,0]
	v_or_b32_e32 v106, 16, v175
	v_mad_i64_i32 v[106:107], s[22:23], v106, s1, v[146:147]
	v_lshl_add_u64 v[114:115], v[106:107], 0, v[148:149]
	v_pk_mul_f32 v[108:109], v[120:121], v[116:117] op_sel_hi:[1,0]
	v_pk_mul_f32 v[106:107], v[118:119], v[116:117] op_sel_hi:[1,0]
	v_pk_mul_f32 v[110:111], v[110:111], v[116:117] op_sel_hi:[1,0]
	v_cvt_pk_bf16_f32 v106, v106, v107
	v_cvt_pk_bf16_f32 v107, v108, v109
	v_cvt_pk_bf16_f32 v108, v110, v111
	v_cvt_pk_bf16_f32 v109, v112, v113
	global_store_dwordx4 v[114:115], v[106:109], off
	v_pk_mul_f32 v[104:105], v[104:105], v[116:117] op_sel_hi:[1,0]
	v_pk_mul_f32 v[102:103], v[102:103], v[116:117] op_sel_hi:[1,0]
	v_pk_mul_f32 v[106:107], v[96:97], v[116:117] op_sel_hi:[1,0]
	v_pk_mul_f32 v[96:97], v[94:95], v[116:117] op_sel_hi:[1,0]
	v_cvt_pk_bf16_f32 v94, v102, v103
	v_cvt_pk_bf16_f32 v95, v104, v105
	v_cvt_pk_bf16_f32 v96, v96, v97
	v_cvt_pk_bf16_f32 v97, v106, v107
	global_store_dwordx4 v[114:115], v[94:97], off offset:256
	ds_read2_b32 v[94:95], v182 offset0:32 offset1:48
	s_andn2_b64 vcc, exec, s[38:39]
	v_or_b32_e32 v96, 32, v175
	v_mad_i64_i32 v[96:97], s[22:23], v96, s1, v[146:147]
	s_waitcnt lgkmcnt(0)
	v_pk_mul_f32 v[100:101], v[100:101], v[94:95] op_sel_hi:[1,0]
	v_pk_mul_f32 v[98:99], v[98:99], v[94:95] op_sel_hi:[1,0]
	v_pk_mul_f32 v[102:103], v[92:93], v[94:95] op_sel_hi:[1,0]
	v_pk_mul_f32 v[92:93], v[90:91], v[94:95] op_sel_hi:[1,0]
	v_lshl_add_u64 v[96:97], v[96:97], 0, v[148:149]
	v_cvt_pk_bf16_f32 v90, v98, v99
	v_cvt_pk_bf16_f32 v91, v100, v101
	v_cvt_pk_bf16_f32 v92, v92, v93
	v_cvt_pk_bf16_f32 v93, v102, v103
	global_store_dwordx4 v[96:97], v[90:93], off
	v_pk_mul_f32 v[84:85], v[84:85], v[94:95] op_sel_hi:[1,0]
	v_pk_mul_f32 v[82:83], v[82:83], v[94:95] op_sel_hi:[1,0]
	v_pk_mul_f32 v[90:91], v[76:77], v[94:95] op_sel_hi:[1,0]
	v_pk_mul_f32 v[76:77], v[74:75], v[94:95] op_sel_hi:[1,0]
	v_cvt_pk_bf16_f32 v74, v82, v83
	v_cvt_pk_bf16_f32 v75, v84, v85
	v_cvt_pk_bf16_f32 v76, v76, v77
	v_cvt_pk_bf16_f32 v77, v90, v91
	global_store_dwordx4 v[96:97], v[74:77], off offset:256
	v_mov_b32_e32 v84, v95
	v_pk_mul_f32 v[80:81], v[80:81], v[84:85] op_sel_hi:[1,0]
	v_or_b32_e32 v74, 48, v175
	v_mad_i64_i32 v[74:75], s[22:23], v74, s1, v[146:147]
	v_lshl_add_u64 v[82:83], v[74:75], 0, v[148:149]
	v_pk_mul_f32 v[76:77], v[88:89], v[84:85] op_sel_hi:[1,0]
	v_pk_mul_f32 v[74:75], v[86:87], v[84:85] op_sel_hi:[1,0]
	v_pk_mul_f32 v[78:79], v[78:79], v[84:85] op_sel_hi:[1,0]
	v_cvt_pk_bf16_f32 v74, v74, v75
	v_cvt_pk_bf16_f32 v75, v76, v77
	v_cvt_pk_bf16_f32 v76, v78, v79
	v_cvt_pk_bf16_f32 v77, v80, v81
	global_store_dwordx4 v[82:83], v[74:77], off
	v_pk_mul_f32 v[72:73], v[72:73], v[84:85] op_sel_hi:[1,0]
	v_pk_mul_f32 v[70:71], v[70:71], v[84:85] op_sel_hi:[1,0]
	v_pk_mul_f32 v[74:75], v[68:69], v[84:85] op_sel_hi:[1,0]
	v_pk_mul_f32 v[68:69], v[66:67], v[84:85] op_sel_hi:[1,0]
	v_cvt_pk_bf16_f32 v66, v70, v71
	v_cvt_pk_bf16_f32 v67, v72, v73
	v_cvt_pk_bf16_f32 v68, v68, v69
	v_cvt_pk_bf16_f32 v69, v74, v75
	global_store_dwordx4 v[82:83], v[66:69], off offset:256
	ds_read2_b32 v[66:67], v182 offset0:128 offset1:144
	s_mov_b64 s[28:29], -1
	v_add_u32_e32 v68, 0x80, v175
	v_mad_i64_i32 v[68:69], s[22:23], v68, s1, v[146:147]
	s_waitcnt lgkmcnt(0)
; DI unsigned pack2(float lo, float hi) { f32x2_t v = {lo, hi}; return __builtin_bit_cast(unsigned, __builtin_convertvector(v, bf16x2_t)); }
; #define PG8_LAS __attribute__((address_space(3)))
; #define PG8_RTAB_LOAD(var, unit) do { if constexpr (Epi::NEEDS_R) { var = *(const uint4*)(E.ssq + (size_t)((unit).pm * BM + (tid >> 1)) * 16 + (tid & 1) * 8); } } while (0)
; #define PG8_RTAB_FIN(var, buf) do { if constexpr (Epi::NEEDS_R) { float ss_ = bflo(var.x) + bfhi(var.x) + bflo(var.y) + bfhi(var.y) + bflo(var.z) + bfhi(var.z) + bflo(var.w) + bfhi(var.w); ss_ += __shfl_xor(ss_, 1); \
;     if (!(tid & 1)) ((PG8_LAS float*)(lds + RT_OFF))[(buf) * 256 + (tid >> 1)] = rsqrtf(ss_ * (1.0f / DM) + EPS); } } while (0)
;   DI void operator()(const f32x4 (&acc)[2][2][4][2], const Unit& u, int wr, int wc, int fr, int fq, const PG8_LAS float* rt) const {
;     ...
;         for (int bj = 0; bj < 2; ++bj) { const f32x4 v0 = acc[ai][bj][m][0] * r, v1 = acc[ai][bj][m][1] * r;
;           u32x4 w; w.x = pack2(v0[0], v0[1]); w.y = pack2(v0[2], v0[3]); w.z = pack2(v1[0], v1[1]); w.w = pack2(v1[2], v1[3]);
;           *(u32x4*)(rowp + bj * HALF) = w; } }
; template <class Epi>
; DI void gemm_phase(const bf16_t* __restrict__ gA, const bf16_t* __restrict__ gBt, int M, int N, int K, const Epi& E, char* lds_generic) {
;     ...
;     uint4 rtn_ = {0u, 0u, 0u, 0u};
;     if (has_next) PG8_RTAB_LOAD(rtn_, nxt);
;     E(acc, cur, wr, wc, fr, fq, (const PG8_LAS float*)(lds + RT_OFF) + (ui & 1) * 256);
;     if (!has_next) break;
;     PG8_RTAB_FIN(rtn_, (ui + 1) & 1);
	v_pk_mul_f32 v[64:65], v[64:65], v[66:67] op_sel_hi:[1,0]
	v_pk_mul_f32 v[62:63], v[62:63], v[66:67] op_sel_hi:[1,0]
	v_pk_mul_f32 v[70:71], v[60:61], v[66:67] op_sel_hi:[1,0]
	v_pk_mul_f32 v[60:61], v[58:59], v[66:67] op_sel_hi:[1,0]
	v_lshl_add_u64 v[68:69], v[68:69], 0, v[148:149]
	v_cvt_pk_bf16_f32 v58, v62, v63
	v_cvt_pk_bf16_f32 v59, v64, v65
	v_cvt_pk_bf16_f32 v60, v60, v61
	v_cvt_pk_bf16_f32 v61, v70, v71
	global_store_dwordx4 v[68:69], v[58:61], off
	v_pk_mul_f32 v[52:53], v[52:53], v[66:67] op_sel_hi:[1,0]
	v_pk_mul_f32 v[50:51], v[50:51], v[66:67] op_sel_hi:[1,0]
	v_pk_mul_f32 v[58:59], v[44:45], v[66:67] op_sel_hi:[1,0]
	v_pk_mul_f32 v[44:45], v[42:43], v[66:67] op_sel_hi:[1,0]
	v_cvt_pk_bf16_f32 v42, v50, v51
	v_cvt_pk_bf16_f32 v43, v52, v53
	v_cvt_pk_bf16_f32 v44, v44, v45
	v_cvt_pk_bf16_f32 v45, v58, v59
	global_store_dwordx4 v[68:69], v[42:45], off offset:256
	v_mov_b32_e32 v52, v67
	v_pk_mul_f32 v[48:49], v[48:49], v[52:53] op_sel_hi:[1,0]
	v_add_u32_e32 v42, 0x90, v175
	v_mad_i64_i32 v[42:43], s[22:23], v42, s1, v[146:147]
	v_lshl_add_u64 v[50:51], v[42:43], 0, v[148:149]
	v_pk_mul_f32 v[44:45], v[56:57], v[52:53] op_sel_hi:[1,0]
	v_pk_mul_f32 v[42:43], v[54:55], v[52:53] op_sel_hi:[1,0]
	v_pk_mul_f32 v[46:47], v[46:47], v[52:53] op_sel_hi:[1,0]
	v_cvt_pk_bf16_f32 v42, v42, v43
	v_cvt_pk_bf16_f32 v43, v44, v45
	v_cvt_pk_bf16_f32 v44, v46, v47
	v_cvt_pk_bf16_f32 v45, v48, v49
	global_store_dwordx4 v[50:51], v[42:45], off
	v_pk_mul_f32 v[40:41], v[40:41], v[52:53] op_sel_hi:[1,0]
	v_pk_mul_f32 v[38:39], v[38:39], v[52:53] op_sel_hi:[1,0]
	v_pk_mul_f32 v[42:43], v[32:33], v[52:53] op_sel_hi:[1,0]
	v_pk_mul_f32 v[32:33], v[30:31], v[52:53] op_sel_hi:[1,0]
	v_cvt_pk_bf16_f32 v30, v38, v39
	v_cvt_pk_bf16_f32 v31, v40, v41
	v_cvt_pk_bf16_f32 v32, v32, v33
	v_cvt_pk_bf16_f32 v33, v42, v43
	global_store_dwordx4 v[50:51], v[30:33], off offset:256
	ds_read2_b32 v[30:31], v182 offset0:160 offset1:176
	s_waitcnt lgkmcnt(0)
	v_pk_mul_f32 v[36:37], v[36:37], v[30:31] op_sel_hi:[1,0]
	v_add_u32_e32 v32, 0xa0, v175
	v_mad_i64_i32 v[32:33], s[22:23], v32, s1, v[146:147]
	v_pk_mul_f32 v[34:35], v[34:35], v[30:31] op_sel_hi:[1,0]
	v_pk_mul_f32 v[38:39], v[28:29], v[30:31] op_sel_hi:[1,0]
	v_pk_mul_f32 v[28:29], v[26:27], v[30:31] op_sel_hi:[1,0]
	v_lshl_add_u64 v[32:33], v[32:33], 0, v[148:149]
	v_cvt_pk_bf16_f32 v26, v34, v35
	v_cvt_pk_bf16_f32 v27, v36, v37
	v_cvt_pk_bf16_f32 v28, v28, v29
	v_cvt_pk_bf16_f32 v29, v38, v39
	global_store_dwordx4 v[32:33], v[26:29], off
	v_pk_mul_f32 v[20:21], v[20:21], v[30:31] op_sel_hi:[1,0]
	v_pk_mul_f32 v[18:19], v[18:19], v[30:31] op_sel_hi:[1,0]
	v_pk_mul_f32 v[26:27], v[12:13], v[30:31] op_sel_hi:[1,0]
	v_pk_mul_f32 v[12:13], v[10:11], v[30:31] op_sel_hi:[1,0]
	v_cvt_pk_bf16_f32 v10, v18, v19
	v_cvt_pk_bf16_f32 v11, v20, v21
	v_cvt_pk_bf16_f32 v12, v12, v13
	v_cvt_pk_bf16_f32 v13, v26, v27
	global_store_dwordx4 v[32:33], v[10:13], off offset:256
	v_mov_b32_e32 v20, v31
	v_pk_mul_f32 v[16:17], v[16:17], v[20:21] op_sel_hi:[1,0]
	v_add_u32_e32 v10, 0xb0, v175
	v_mad_i64_i32 v[10:11], s[22:23], v10, s1, v[146:147]
	v_lshl_add_u64 v[18:19], v[10:11], 0, v[148:149]
	v_pk_mul_f32 v[12:13], v[24:25], v[20:21] op_sel_hi:[1,0]
	v_pk_mul_f32 v[10:11], v[22:23], v[20:21] op_sel_hi:[1,0]
	v_pk_mul_f32 v[14:15], v[14:15], v[20:21] op_sel_hi:[1,0]
	v_cvt_pk_bf16_f32 v10, v10, v11
	v_cvt_pk_bf16_f32 v11, v12, v13
	v_cvt_pk_bf16_f32 v12, v14, v15
	v_cvt_pk_bf16_f32 v13, v16, v17
	global_store_dwordx4 v[18:19], v[10:13], off
	v_pk_mul_f32 v[8:9], v[8:9], v[20:21] op_sel_hi:[1,0]
	v_pk_mul_f32 v[6:7], v[6:7], v[20:21] op_sel_hi:[1,0]
	v_pk_mul_f32 v[10:11], v[4:5], v[20:21] op_sel_hi:[1,0]
	v_pk_mul_f32 v[4:5], v[2:3], v[20:21] op_sel_hi:[1,0]
	v_cvt_pk_bf16_f32 v2, v6, v7
	v_cvt_pk_bf16_f32 v3, v8, v9
	v_cvt_pk_bf16_f32 v4, v4, v5
	v_cvt_pk_bf16_f32 v5, v10, v11
	global_store_dwordx4 v[18:19], v[2:5], off offset:256
	s_cbranch_vccnz .LBB0_133
	s_waitcnt vmcnt(16)
	v_lshlrev_b32_e32 v2, 16, v130
	v_and_b32_e32 v3, 0xffff0000, v130
	v_add_f32_e32 v2, v2, v3
	v_lshlrev_b32_e32 v3, 16, v131
	v_add_f32_e32 v2, v2, v3
	v_and_b32_e32 v3, 0xffff0000, v131
	v_add_f32_e32 v2, v2, v3
	v_lshlrev_b32_e32 v3, 16, v132
	v_add_f32_e32 v2, v2, v3
	v_and_b32_e32 v3, 0xffff0000, v132
	v_add_f32_e32 v2, v2, v3
	v_lshlrev_b32_e32 v3, 16, v133
	v_add_f32_e32 v2, v2, v3
	v_and_b32_e32 v3, 0xffff0000, v133
	v_add_f32_e32 v2, v2, v3
	ds_bpermute_b32 v3, v151, v2
	s_and_saveexec_b64 s[22:23], s[36:37]
	s_xor_b64 s[28:29], exec, s[22:23]
	s_cbranch_execz .LBB0_132
	s_waitcnt lgkmcnt(0)
	v_add_f32_e32 v2, v2, v3
	v_fmamk_f32 v2, v2, 0x3a800000, v234
	v_cmp_gt_f32_e32 vcc, s97, v2
	v_mul_f32_e32 v3, 0x4b800000, v2
	s_lshl_b32 s1, s42, 10
	v_cndmask_b32_e32 v2, v2, v3, vcc
	v_rsq_f32_e32 v2, v2
	s_and_b32 s1, s1, 0x400
	v_mul_f32_e32 v3, 0x45800000, v2
	v_cndmask_b32_e32 v2, v2, v3, vcc
	v_add_u32_e32 v3, s1, v152
	ds_write_b32 v3, v2
	s_branch .LBB0_132

; DI unsigned pack2(float lo, float hi) { f32x2_t v = {lo, hi}; return __builtin_bit_cast(unsigned, __builtin_convertvector(v, bf16x2_t)); }
; #define PG8_LAS __attribute__((address_space(3)))
;   DI void operator()(const f32x4 (&acc)[2][2][4][2], const Unit& u, int wr, int wc, int fr, int fq, const PG8_LAS float* rt) const {
;     const int row0 = u.pm * BM + wr * 64 + fr, col0 = u.pn * BM + wc * 32 + 8 * fq;
; #pragma unroll
;     for (int ai = 0; ai < 2; ++ai)
; #pragma unroll
;       for (int m = 0; m < 4; ++m) { bf16_t* rowp = O + (size_t)(row0 + ai * HALF + m * 16) * ldc + col0; const float r = rt[ai * HALF + wr * 64 + m * 16 + fr];
; #pragma unroll
;         for (int bj = 0; bj < 2; ++bj) { const f32x4 v0 = acc[ai][bj][m][0] * r, v1 = acc[ai][bj][m][1] * r;
;           u32x4 w; w.x = pack2(v0[0], v0[1]); w.y = pack2(v0[2], v0[3]); w.z = pack2(v1[0], v1[1]); w.w = pack2(v1[2], v1[3]);
;           *(u32x4*)(rowp + bj * HALF) = w; } }
.LBB0_162:
	s_lshl_b32 s1, s42, 10
	s_and_b32 s1, s1, 0x400
	v_add_u32_e32 v165, s1, v156
	ds_read2_b32 v[158:159], v165 offset1:16
	v_lshl_or_b32 v148, s35, 8, v157
	v_lshl_add_u32 v163, s53, 8, v153
	v_ashrrev_i32_e32 v149, 31, v148
	v_mov_b64_e32 v[146:147], s[66:67]
	s_movk_i32 s1, 0x1200
	v_mad_i64_i32 v[160:161], s[22:23], v163, s1, v[146:147]
	v_lshlrev_b64 v[148:149], 1, v[148:149]
	s_waitcnt lgkmcnt(0)
	v_pk_mul_f32 v[128:129], v[128:129], v[158:159] op_sel_hi:[1,0]
	v_pk_mul_f32 v[126:127], v[126:127], v[158:159] op_sel_hi:[1,0]
	v_pk_mul_f32 v[166:167], v[124:125], v[158:159] op_sel_hi:[1,0]
	v_pk_mul_f32 v[124:125], v[122:123], v[158:159] op_sel_hi:[1,0]
	v_lshl_add_u64 v[160:161], v[160:161], 0, v[148:149]
	v_cvt_pk_bf16_f32 v122, v126, v127
	v_cvt_pk_bf16_f32 v123, v128, v129
	v_cvt_pk_bf16_f32 v124, v124, v125
	v_cvt_pk_bf16_f32 v125, v166, v167
	global_store_dwordx4 v[160:161], v[122:125], off
	v_pk_mul_f32 v[116:117], v[116:117], v[158:159] op_sel_hi:[1,0]
	v_pk_mul_f32 v[114:115], v[114:115], v[158:159] op_sel_hi:[1,0]
	v_pk_mul_f32 v[122:123], v[108:109], v[158:159] op_sel_hi:[1,0]
	v_pk_mul_f32 v[108:109], v[106:107], v[158:159] op_sel_hi:[1,0]
	v_cvt_pk_bf16_f32 v106, v114, v115
	v_cvt_pk_bf16_f32 v107, v116, v117
	v_cvt_pk_bf16_f32 v108, v108, v109
	v_cvt_pk_bf16_f32 v109, v122, v123
	global_store_dwordx4 v[160:161], v[106:109], off offset:256
	v_mov_b32_e32 v116, v159
	v_pk_mul_f32 v[112:113], v[112:113], v[116:117] op_sel_hi:[1,0]
	v_or_b32_e32 v106, 16, v163
	v_mad_i64_i32 v[106:107], s[22:23], v106, s1, v[146:147]
	v_lshl_add_u64 v[114:115], v[106:107], 0, v[148:149]
	v_pk_mul_f32 v[108:109], v[120:121], v[116:117] op_sel_hi:[1,0]
	v_pk_mul_f32 v[106:107], v[118:119], v[116:117] op_sel_hi:[1,0]
	v_pk_mul_f32 v[110:111], v[110:111], v[116:117] op_sel_hi:[1,0]
	v_cvt_pk_bf16_f32 v106, v106, v107
	v_cvt_pk_bf16_f32 v107, v108, v109
	v_cvt_pk_bf16_f32 v108, v110, v111
	v_cvt_pk_bf16_f32 v109, v112, v113
	global_store_dwordx4 v[114:115], v[106:109], off
	v_pk_mul_f32 v[104:105], v[104:105], v[116:117] op_sel_hi:[1,0]
	v_pk_mul_f32 v[102:103], v[102:103], v[116:117] op_sel_hi:[1,0]
	v_pk_mul_f32 v[106:107], v[96:97], v[116:117] op_sel_hi:[1,0]
	v_pk_mul_f32 v[96:97], v[94:95], v[116:117] op_sel_hi:[1,0]
	v_cvt_pk_bf16_f32 v94, v102, v103
	v_cvt_pk_bf16_f32 v95, v104, v105
	v_cvt_pk_bf16_f32 v96, v96, v97
	v_cvt_pk_bf16_f32 v97, v106, v107
	global_store_dwordx4 v[114:115], v[94:97], off offset:256
	ds_read2_b32 v[94:95], v165 offset0:32 offset1:48
	s_andn2_b64 vcc, exec, s[38:39]
	v_or_b32_e32 v96, 32, v163
	v_mad_i64_i32 v[96:97], s[22:23], v96, s1, v[146:147]
	s_waitcnt lgkmcnt(0)
	v_pk_mul_f32 v[100:101], v[100:101], v[94:95] op_sel_hi:[1,0]
	v_pk_mul_f32 v[98:99], v[98:99], v[94:95] op_sel_hi:[1,0]
	v_pk_mul_f32 v[102:103], v[92:93], v[94:95] op_sel_hi:[1,0]
	v_pk_mul_f32 v[92:93], v[90:91], v[94:95] op_sel_hi:[1,0]
	v_lshl_add_u64 v[96:97], v[96:97], 0, v[148:149]
	v_cvt_pk_bf16_f32 v90, v98, v99
	v_cvt_pk_bf16_f32 v91, v100, v101
	v_cvt_pk_bf16_f32 v92, v92, v93
	v_cvt_pk_bf16_f32 v93, v102, v103
	global_store_dwordx4 v[96:97], v[90:93], off
	v_pk_mul_f32 v[84:85], v[84:85], v[94:95] op_sel_hi:[1,0]
	v_pk_mul_f32 v[82:83], v[82:83], v[94:95] op_sel_hi:[1,0]
	v_pk_mul_f32 v[90:91], v[76:77], v[94:95] op_sel_hi:[1,0]
	v_pk_mul_f32 v[76:77], v[74:75], v[94:95] op_sel_hi:[1,0]
	v_cvt_pk_bf16_f32 v74, v82, v83
	v_cvt_pk_bf16_f32 v75, v84, v85
	v_cvt_pk_bf16_f32 v76, v76, v77
	v_cvt_pk_bf16_f32 v77, v90, v91
	global_store_dwordx4 v[96:97], v[74:77], off offset:256
	v_mov_b32_e32 v84, v95
	v_pk_mul_f32 v[80:81], v[80:81], v[84:85] op_sel_hi:[1,0]
	v_or_b32_e32 v74, 48, v163
	v_mad_i64_i32 v[74:75], s[22:23], v74, s1, v[146:147]
	v_lshl_add_u64 v[82:83], v[74:75], 0, v[148:149]
	v_pk_mul_f32 v[76:77], v[88:89], v[84:85] op_sel_hi:[1,0]
	v_pk_mul_f32 v[74:75], v[86:87], v[84:85] op_sel_hi:[1,0]
	v_pk_mul_f32 v[78:79], v[78:79], v[84:85] op_sel_hi:[1,0]
	v_cvt_pk_bf16_f32 v74, v74, v75
	v_cvt_pk_bf16_f32 v75, v76, v77
	v_cvt_pk_bf16_f32 v76, v78, v79
	v_cvt_pk_bf16_f32 v77, v80, v81
	global_store_dwordx4 v[82:83], v[74:77], off
	v_pk_mul_f32 v[72:73], v[72:73], v[84:85] op_sel_hi:[1,0]
	v_pk_mul_f32 v[70:71], v[70:71], v[84:85] op_sel_hi:[1,0]
	v_pk_mul_f32 v[74:75], v[68:69], v[84:85] op_sel_hi:[1,0]
	v_pk_mul_f32 v[68:69], v[66:67], v[84:85] op_sel_hi:[1,0]
	v_cvt_pk_bf16_f32 v66, v70, v71
	v_cvt_pk_bf16_f32 v67, v72, v73
	v_cvt_pk_bf16_f32 v68, v68, v69
	v_cvt_pk_bf16_f32 v69, v74, v75
	global_store_dwordx4 v[82:83], v[66:69], off offset:256
	ds_read2_b32 v[66:67], v165 offset0:128 offset1:144
	s_mov_b64 s[28:29], -1
	v_add_u32_e32 v68, 0x80, v163
	v_mad_i64_i32 v[68:69], s[22:23], v68, s1, v[146:147]
	s_waitcnt lgkmcnt(0)
; DI unsigned pack2(float lo, float hi) { f32x2_t v = {lo, hi}; return __builtin_bit_cast(unsigned, __builtin_convertvector(v, bf16x2_t)); }
; #define PG8_LAS __attribute__((address_space(3)))
; #define PG8_RTAB_LOAD(var, unit) do { if constexpr (Epi::NEEDS_R) { var = *(const uint4*)(E.ssq + (size_t)((unit).pm * BM + (tid >> 1)) * 16 + (tid & 1) * 8); } } while (0)
; #define PG8_RTAB_FIN(var, buf) do { if constexpr (Epi::NEEDS_R) { float ss_ = bflo(var.x) + bfhi(var.x) + bflo(var.y) + bfhi(var.y) + bflo(var.z) + bfhi(var.z) + bflo(var.w) + bfhi(var.w); ss_ += __shfl_xor(ss_, 1); \
;     if (!(tid & 1)) ((PG8_LAS float*)(lds + RT_OFF))[(buf) * 256 + (tid >> 1)] = rsqrtf(ss_ * (1.0f / DM) + EPS); } } while (0)
;   DI void operator()(const f32x4 (&acc)[2][2][4][2], const Unit& u, int wr, int wc, int fr, int fq, const PG8_LAS float* rt) const {
;     ...
;         for (int bj = 0; bj < 2; ++bj) { const f32x4 v0 = acc[ai][bj][m][0] * r, v1 = acc[ai][bj][m][1] * r;
;           u32x4 w; w.x = pack2(v0[0], v0[1]); w.y = pack2(v0[2], v0[3]); w.z = pack2(v1[0], v1[1]); w.w = pack2(v1[2], v1[3]);
;           *(u32x4*)(rowp + bj * HALF) = w; } }
; template <class Epi>
; DI void gemm_phase(const bf16_t* __restrict__ gA, const bf16_t* __restrict__ gBt, int M, int N, int K, const Epi& E, char* lds_generic) {
;     ...
;     uint4 rtn_ = {0u, 0u, 0u, 0u};
;     if (has_next) PG8_RTAB_LOAD(rtn_, nxt);
;     E(acc, cur, wr, wc, fr, fq, (const PG8_LAS float*)(lds + RT_OFF) + (ui & 1) * 256);
;     if (!has_next) break;
;     PG8_RTAB_FIN(rtn_, (ui + 1) & 1);
	v_pk_mul_f32 v[64:65], v[64:65], v[66:67] op_sel_hi:[1,0]
	v_pk_mul_f32 v[62:63], v[62:63], v[66:67] op_sel_hi:[1,0]
	v_pk_mul_f32 v[70:71], v[60:61], v[66:67] op_sel_hi:[1,0]
	v_pk_mul_f32 v[60:61], v[58:59], v[66:67] op_sel_hi:[1,0]
	v_lshl_add_u64 v[68:69], v[68:69], 0, v[148:149]
	v_cvt_pk_bf16_f32 v58, v62, v63
	v_cvt_pk_bf16_f32 v59, v64, v65
	v_cvt_pk_bf16_f32 v60, v60, v61
	v_cvt_pk_bf16_f32 v61, v70, v71
	global_store_dwordx4 v[68:69], v[58:61], off
	v_pk_mul_f32 v[52:53], v[52:53], v[66:67] op_sel_hi:[1,0]
	v_pk_mul_f32 v[50:51], v[50:51], v[66:67] op_sel_hi:[1,0]
	v_pk_mul_f32 v[58:59], v[44:45], v[66:67] op_sel_hi:[1,0]
	v_pk_mul_f32 v[44:45], v[42:43], v[66:67] op_sel_hi:[1,0]
	v_cvt_pk_bf16_f32 v42, v50, v51
	v_cvt_pk_bf16_f32 v43, v52, v53
	v_cvt_pk_bf16_f32 v44, v44, v45
	v_cvt_pk_bf16_f32 v45, v58, v59
	global_store_dwordx4 v[68:69], v[42:45], off offset:256
	v_mov_b32_e32 v52, v67
	v_pk_mul_f32 v[48:49], v[48:49], v[52:53] op_sel_hi:[1,0]
	v_add_u32_e32 v42, 0x90, v163
	v_mad_i64_i32 v[42:43], s[22:23], v42, s1, v[146:147]
	v_lshl_add_u64 v[50:51], v[42:43], 0, v[148:149]
	v_pk_mul_f32 v[44:45], v[56:57], v[52:53] op_sel_hi:[1,0]
	v_pk_mul_f32 v[42:43], v[54:55], v[52:53] op_sel_hi:[1,0]
	v_pk_mul_f32 v[46:47], v[46:47], v[52:53] op_sel_hi:[1,0]
	v_cvt_pk_bf16_f32 v42, v42, v43
	v_cvt_pk_bf16_f32 v43, v44, v45
	v_cvt_pk_bf16_f32 v44, v46, v47
	v_cvt_pk_bf16_f32 v45, v48, v49
	global_store_dwordx4 v[50:51], v[42:45], off
	v_pk_mul_f32 v[40:41], v[40:41], v[52:53] op_sel_hi:[1,0]
	v_pk_mul_f32 v[38:39], v[38:39], v[52:53] op_sel_hi:[1,0]
	v_pk_mul_f32 v[42:43], v[32:33], v[52:53] op_sel_hi:[1,0]
	v_pk_mul_f32 v[32:33], v[30:31], v[52:53] op_sel_hi:[1,0]
	v_cvt_pk_bf16_f32 v30, v38, v39
	v_cvt_pk_bf16_f32 v31, v40, v41
	v_cvt_pk_bf16_f32 v32, v32, v33
	v_cvt_pk_bf16_f32 v33, v42, v43
	global_store_dwordx4 v[50:51], v[30:33], off offset:256
	ds_read2_b32 v[30:31], v165 offset0:160 offset1:176
	s_waitcnt lgkmcnt(0)
	v_pk_mul_f32 v[36:37], v[36:37], v[30:31] op_sel_hi:[1,0]
	v_add_u32_e32 v32, 0xa0, v163
	v_mad_i64_i32 v[32:33], s[22:23], v32, s1, v[146:147]
	v_pk_mul_f32 v[34:35], v[34:35], v[30:31] op_sel_hi:[1,0]
	v_pk_mul_f32 v[38:39], v[28:29], v[30:31] op_sel_hi:[1,0]
	v_pk_mul_f32 v[28:29], v[26:27], v[30:31] op_sel_hi:[1,0]
	v_lshl_add_u64 v[32:33], v[32:33], 0, v[148:149]
	v_cvt_pk_bf16_f32 v26, v34, v35
	v_cvt_pk_bf16_f32 v27, v36, v37
	v_cvt_pk_bf16_f32 v28, v28, v29
	v_cvt_pk_bf16_f32 v29, v38, v39
	global_store_dwordx4 v[32:33], v[26:29], off
	v_pk_mul_f32 v[20:21], v[20:21], v[30:31] op_sel_hi:[1,0]
	v_pk_mul_f32 v[18:19], v[18:19], v[30:31] op_sel_hi:[1,0]
	v_pk_mul_f32 v[26:27], v[12:13], v[30:31] op_sel_hi:[1,0]
	v_pk_mul_f32 v[12:13], v[10:11], v[30:31] op_sel_hi:[1,0]
	v_cvt_pk_bf16_f32 v10, v18, v19
	v_cvt_pk_bf16_f32 v11, v20, v21
	v_cvt_pk_bf16_f32 v12, v12, v13
	v_cvt_pk_bf16_f32 v13, v26, v27
	global_store_dwordx4 v[32:33], v[10:13], off offset:256
	v_mov_b32_e32 v20, v31
	v_pk_mul_f32 v[16:17], v[16:17], v[20:21] op_sel_hi:[1,0]
	v_add_u32_e32 v10, 0xb0, v163
	v_mad_i64_i32 v[10:11], s[22:23], v10, s1, v[146:147]
	v_lshl_add_u64 v[18:19], v[10:11], 0, v[148:149]
	v_pk_mul_f32 v[12:13], v[24:25], v[20:21] op_sel_hi:[1,0]
	v_pk_mul_f32 v[10:11], v[22:23], v[20:21] op_sel_hi:[1,0]
	v_pk_mul_f32 v[14:15], v[14:15], v[20:21] op_sel_hi:[1,0]
	v_cvt_pk_bf16_f32 v10, v10, v11
	v_cvt_pk_bf16_f32 v11, v12, v13
	v_cvt_pk_bf16_f32 v12, v14, v15
	v_cvt_pk_bf16_f32 v13, v16, v17
	global_store_dwordx4 v[18:19], v[10:13], off
	v_pk_mul_f32 v[8:9], v[8:9], v[20:21] op_sel_hi:[1,0]
	v_pk_mul_f32 v[6:7], v[6:7], v[20:21] op_sel_hi:[1,0]
	v_pk_mul_f32 v[10:11], v[4:5], v[20:21] op_sel_hi:[1,0]
	v_pk_mul_f32 v[4:5], v[2:3], v[20:21] op_sel_hi:[1,0]
	v_cvt_pk_bf16_f32 v2, v6, v7
	v_cvt_pk_bf16_f32 v3, v8, v9
	v_cvt_pk_bf16_f32 v4, v4, v5
	v_cvt_pk_bf16_f32 v5, v10, v11
	global_store_dwordx4 v[18:19], v[2:5], off offset:256
	s_cbranch_vccnz .LBB0_155
	s_waitcnt vmcnt(16)
	v_lshlrev_b32_e32 v2, 16, v130
	v_and_b32_e32 v3, 0xffff0000, v130
	v_add_f32_e32 v2, v2, v3
	v_lshlrev_b32_e32 v3, 16, v131
	v_add_f32_e32 v2, v2, v3
	v_and_b32_e32 v3, 0xffff0000, v131
	v_add_f32_e32 v2, v2, v3
	v_lshlrev_b32_e32 v3, 16, v132
	v_add_f32_e32 v2, v2, v3
	v_and_b32_e32 v3, 0xffff0000, v132
	v_add_f32_e32 v2, v2, v3
	v_lshlrev_b32_e32 v3, 16, v133
	v_add_f32_e32 v2, v2, v3
	v_and_b32_e32 v3, 0xffff0000, v133
	v_add_f32_e32 v2, v2, v3
	ds_bpermute_b32 v3, v151, v2
	s_and_saveexec_b64 s[22:23], s[36:37]
	s_xor_b64 s[28:29], exec, s[22:23]
	s_cbranch_execz .LBB0_154
	s_waitcnt lgkmcnt(0)
	v_add_f32_e32 v2, v2, v3
	v_fmamk_f32 v2, v2, 0x3a800000, v234
	v_cmp_gt_f32_e32 vcc, s97, v2
	v_mul_f32_e32 v3, 0x4b800000, v2
	s_lshl_b32 s1, s33, 10
	v_cndmask_b32_e32 v2, v2, v3, vcc
	v_rsq_f32_e32 v2, v2
	s_and_b32 s1, s1, 0x400
	v_mul_f32_e32 v3, 0x45800000, v2
	v_cndmask_b32_e32 v2, v2, v3, vcc
	v_add_u32_e32 v3, s1, v152
	ds_write_b32 v3, v2
	s_branch .LBB0_154

; DI unsigned pack2(float lo, float hi) { f32x2_t v = {lo, hi}; return __builtin_bit_cast(unsigned, __builtin_convertvector(v, bf16x2_t)); }
; #define PG8_LAS __attribute__((address_space(3)))
;   DI void operator()(const f32x4 (&acc)[2][2][4][2], const Unit& u, int wr, int wc, int fr, int fq, const PG8_LAS float* rt) const {
;     const int row0 = u.pm * BM + wr * 64 + fr, col0 = u.pn * HALF + wc * 32 + 8 * fq;
; #pragma unroll
;     for (int ai = 0; ai < 2; ++ai)
; #pragma unroll
;       for (int m = 0; m < 4; ++m) {
;         const float r = rt[ai * HALF + wr * 64 + m * 16 + fr];
;         float a[8];
; #pragma unroll
;         for (int n = 0; n < 2; ++n)
; #pragma unroll
;           for (int j = 0; j < 4; ++j) { const float u1 = acc[ai][0][m][n][j] * r, u3 = acc[ai][1][m][n][j] * r; a[4 * n + j] = u1 * u3 * __builtin_amdgcn_rcpf(1.f + __builtin_amdgcn_exp2f(-LOG2E * u1)); }
;         u32x4 w; w.x = pack2(a[0], a[1]); w.y = pack2(a[2], a[3]); w.z = pack2(a[4], a[5]); w.w = pack2(a[6], a[7]);
;         *(u32x4*)(O + (size_t)(row0 + ai * HALF + m * 16) * DFF + col0) = w; }
.LBB0_608:
	s_lshl_b32 s8, s8, 10
	s_and_b32 s8, s8, 0x400
	v_add_u32_e32 v159, s8, v156
	ds_read2_b32 v[148:149], v159 offset1:16
	v_lshl_or_b32 v146, s9, 7, v157
	v_lshl_add_u32 v158, s19, 8, v153
	v_ashrrev_i32_e32 v147, 31, v146
	s_mov_b64 s[28:29], -1
	s_waitcnt lgkmcnt(0)
	v_pk_mul_f32 v[130:131], v[130:131], v[148:149] op_sel_hi:[1,0]
	v_pk_mul_f32 v[126:127], v[126:127], v[148:149] op_sel_hi:[1,0]
	v_mul_f32_e32 v160, 0xbfb8aa3b, v130
	v_pk_mul_f32 v[126:127], v[130:131], v[126:127]
	v_mul_f32_e32 v130, 0xbfb8aa3b, v131
	v_exp_f32_e32 v130, v130
	v_pk_mul_f32 v[128:129], v[128:129], v[148:149] op_sel_hi:[1,0]
	v_pk_mul_f32 v[122:123], v[122:123], v[148:149] op_sel_hi:[1,0]
	v_pk_mul_f32 v[118:119], v[118:119], v[148:149] op_sel_hi:[1,0]
	v_add_f32_e32 v130, 1.0, v130
	v_rcp_f32_e32 v161, v130
	v_pk_mul_f32 v[130:131], v[132:133], v[148:149] op_sel_hi:[1,0]
	v_pk_mul_f32 v[118:119], v[122:123], v[118:119]
	v_mul_f32_e32 v132, 0xbfb8aa3b, v130
	v_pk_mul_f32 v[128:129], v[130:131], v[128:129]
	v_mul_f32_e32 v130, 0xbfb8aa3b, v131
	v_exp_f32_e32 v130, v130
	v_pk_mul_f32 v[120:121], v[120:121], v[148:149] op_sel_hi:[1,0]
	v_exp_f32_e32 v160, v160
	v_exp_f32_e32 v132, v132
	v_add_f32_e32 v130, 1.0, v130
	v_rcp_f32_e32 v133, v130
	v_mul_f32_e32 v130, 0xbfb8aa3b, v122
	v_mul_f32_e32 v122, 0xbfb8aa3b, v123
	v_exp_f32_e32 v122, v122
	v_exp_f32_e32 v130, v130
	v_add_f32_e32 v160, 1.0, v160
	v_rcp_f32_e32 v160, v160
	v_add_f32_e32 v122, 1.0, v122
	v_rcp_f32_e32 v131, v122
	v_pk_mul_f32 v[122:123], v[124:125], v[148:149] op_sel_hi:[1,0]
	v_add_f32_e32 v130, 1.0, v130
	v_mul_f32_e32 v124, 0xbfb8aa3b, v122
	v_pk_mul_f32 v[120:121], v[122:123], v[120:121]
	v_mul_f32_e32 v122, 0xbfb8aa3b, v123
	v_exp_f32_e32 v124, v124
	v_exp_f32_e32 v122, v122
	v_rcp_f32_e32 v130, v130
	v_add_f32_e32 v132, 1.0, v132
	v_add_f32_e32 v124, 1.0, v124
	v_add_f32_e32 v122, 1.0, v122
	v_rcp_f32_e32 v124, v124
	v_rcp_f32_e32 v125, v122
	v_rcp_f32_e32 v132, v132
	v_pk_mul_f32 v[118:119], v[118:119], v[130:131]
	v_pk_mul_f32 v[126:127], v[126:127], v[160:161]
	v_pk_mul_f32 v[120:121], v[120:121], v[124:125]
	v_cvt_pk_bf16_f32 v124, v118, v119
	v_mov_b64_e32 v[118:119], s[66:67]
	v_pk_mul_f32 v[128:129], v[128:129], v[132:133]
	v_cvt_pk_bf16_f32 v122, v126, v127
	v_cvt_pk_bf16_f32 v125, v120, v121
	v_mad_i64_i32 v[126:127], s[8:9], v158, s43, v[118:119]
	v_lshlrev_b64 v[120:121], 1, v[146:147]
	v_cvt_pk_bf16_f32 v123, v128, v129
	v_lshl_add_u64 v[126:127], v[126:127], 0, v[120:121]
	global_store_dwordx4 v[126:127], v[122:125], off
	s_andn2_b64 vcc, exec, s[38:39]
	s_nop 0
	v_mov_b32_e32 v122, v149
	v_pk_mul_f32 v[114:115], v[114:115], v[122:123] op_sel_hi:[1,0]
	s_nop 0
	v_mul_f32_e32 v123, 0xbfb8aa3b, v114
	v_exp_f32_e32 v123, v123
	s_nop 0
	v_add_f32_e32 v123, 1.0, v123
	v_pk_mul_f32 v[110:111], v[110:111], v[122:123] op_sel_hi:[1,0]
	v_pk_mul_f32 v[112:113], v[112:113], v[122:123] op_sel_hi:[1,0]
	v_pk_mul_f32 v[110:111], v[114:115], v[110:111]
	v_mul_f32_e32 v114, 0xbfb8aa3b, v115
	v_exp_f32_e32 v114, v114
	v_pk_mul_f32 v[106:107], v[106:107], v[122:123] op_sel_hi:[1,0]
	v_pk_mul_f32 v[102:103], v[102:103], v[122:123] op_sel_hi:[1,0]
	v_pk_mul_f32 v[104:105], v[104:105], v[122:123] op_sel_hi:[1,0]
	v_add_f32_e32 v114, 1.0, v114
	v_rcp_f32_e32 v125, v114
	v_pk_mul_f32 v[114:115], v[116:117], v[122:123] op_sel_hi:[1,0]
	v_pk_mul_f32 v[102:103], v[106:107], v[102:103]
	v_mul_f32_e32 v116, 0xbfb8aa3b, v114
	v_pk_mul_f32 v[112:113], v[114:115], v[112:113]
	v_mul_f32_e32 v114, 0xbfb8aa3b, v115
	v_exp_f32_e32 v114, v114
	v_exp_f32_e32 v116, v116
	v_rcp_f32_e32 v124, v123
	v_add_f32_e32 v114, 1.0, v114
	v_rcp_f32_e32 v117, v114
	v_mul_f32_e32 v114, 0xbfb8aa3b, v106
	v_mul_f32_e32 v106, 0xbfb8aa3b, v107
	v_exp_f32_e32 v114, v114
	v_exp_f32_e32 v106, v106
	v_add_f32_e32 v116, 1.0, v116
	v_rcp_f32_e32 v116, v116
	v_add_f32_e32 v114, 1.0, v114
	v_add_f32_e32 v106, 1.0, v106
	v_rcp_f32_e32 v114, v114
	v_rcp_f32_e32 v115, v106
	v_pk_mul_f32 v[110:111], v[110:111], v[124:125]
	v_pk_mul_f32 v[112:113], v[112:113], v[116:117]
	v_pk_mul_f32 v[106:107], v[102:103], v[114:115]
	v_pk_mul_f32 v[102:103], v[108:109], v[122:123] op_sel_hi:[1,0]
	s_nop 0
	v_mul_f32_e32 v108, 0xbfb8aa3b, v102
	v_pk_mul_f32 v[104:105], v[102:103], v[104:105]
	v_mul_f32_e32 v102, 0xbfb8aa3b, v103
	v_exp_f32_e32 v108, v108
	v_exp_f32_e32 v102, v102
	v_cvt_pk_bf16_f32 v103, v112, v113
	v_add_f32_e32 v108, 1.0, v108
	v_add_f32_e32 v102, 1.0, v102
	v_rcp_f32_e32 v108, v108
	v_rcp_f32_e32 v109, v102
	v_cvt_pk_bf16_f32 v102, v110, v111
	v_pk_mul_f32 v[108:109], v[104:105], v[108:109]
	v_cvt_pk_bf16_f32 v104, v106, v107
	v_or_b32_e32 v106, 16, v158
	v_mad_i64_i32 v[106:107], s[8:9], v106, s43, v[118:119]
	v_cvt_pk_bf16_f32 v105, v108, v109
	v_lshl_add_u64 v[106:107], v[106:107], 0, v[120:121]
	global_store_dwordx4 v[106:107], v[102:105], off
	ds_read2_b32 v[102:103], v159 offset0:32 offset1:48
	s_waitcnt lgkmcnt(0)
; DI unsigned pack2(float lo, float hi) { f32x2_t v = {lo, hi}; return __builtin_bit_cast(unsigned, __builtin_convertvector(v, bf16x2_t)); }
; #define PG8_LAS __attribute__((address_space(3)))
;   DI void operator()(const f32x4 (&acc)[2][2][4][2], const Unit& u, int wr, int wc, int fr, int fq, const PG8_LAS float* rt) const {
;     const int row0 = u.pm * BM + wr * 64 + fr, col0 = u.pn * HALF + wc * 32 + 8 * fq;
; #pragma unroll
;     for (int ai = 0; ai < 2; ++ai)
; #pragma unroll
;       for (int m = 0; m < 4; ++m) {
;         const float r = rt[ai * HALF + wr * 64 + m * 16 + fr];
;         float a[8];
; #pragma unroll
;         for (int n = 0; n < 2; ++n)
; #pragma unroll
;           for (int j = 0; j < 4; ++j) { const float u1 = acc[ai][0][m][n][j] * r, u3 = acc[ai][1][m][n][j] * r; a[4 * n + j] = u1 * u3 * __builtin_amdgcn_rcpf(1.f + __builtin_amdgcn_exp2f(-LOG2E * u1)); }
;         u32x4 w; w.x = pack2(a[0], a[1]); w.y = pack2(a[2], a[3]); w.z = pack2(a[4], a[5]); w.w = pack2(a[6], a[7]);
;         *(u32x4*)(O + (size_t)(row0 + ai * HALF + m * 16) * DFF + col0) = w; }
	v_pk_mul_f32 v[98:99], v[98:99], v[102:103] op_sel_hi:[1,0]
	v_pk_mul_f32 v[94:95], v[94:95], v[102:103] op_sel_hi:[1,0]
	v_mul_f32_e32 v104, 0xbfb8aa3b, v98
	v_pk_mul_f32 v[94:95], v[98:99], v[94:95]
	v_mul_f32_e32 v98, 0xbfb8aa3b, v99
	v_exp_f32_e32 v98, v98
	v_pk_mul_f32 v[96:97], v[96:97], v[102:103] op_sel_hi:[1,0]
	v_pk_mul_f32 v[90:91], v[90:91], v[102:103] op_sel_hi:[1,0]
	v_pk_mul_f32 v[86:87], v[86:87], v[102:103] op_sel_hi:[1,0]
	v_add_f32_e32 v98, 1.0, v98
	v_rcp_f32_e32 v105, v98
	v_pk_mul_f32 v[98:99], v[100:101], v[102:103] op_sel_hi:[1,0]
	v_pk_mul_f32 v[86:87], v[90:91], v[86:87]
	v_mul_f32_e32 v100, 0xbfb8aa3b, v98
	v_pk_mul_f32 v[96:97], v[98:99], v[96:97]
	v_mul_f32_e32 v98, 0xbfb8aa3b, v99
	v_exp_f32_e32 v98, v98
	v_pk_mul_f32 v[88:89], v[88:89], v[102:103] op_sel_hi:[1,0]
	v_exp_f32_e32 v104, v104
	v_exp_f32_e32 v100, v100
	v_add_f32_e32 v98, 1.0, v98
	v_rcp_f32_e32 v101, v98
	v_mul_f32_e32 v98, 0xbfb8aa3b, v90
	v_mul_f32_e32 v90, 0xbfb8aa3b, v91
	v_exp_f32_e32 v98, v98
	v_exp_f32_e32 v90, v90
	v_add_f32_e32 v104, 1.0, v104
	v_add_f32_e32 v100, 1.0, v100
	v_add_f32_e32 v98, 1.0, v98
	v_add_f32_e32 v90, 1.0, v90
	v_rcp_f32_e32 v98, v98
	v_rcp_f32_e32 v99, v90
	v_rcp_f32_e32 v104, v104
	v_rcp_f32_e32 v100, v100
	v_pk_mul_f32 v[90:91], v[86:87], v[98:99]
	v_pk_mul_f32 v[86:87], v[92:93], v[102:103] op_sel_hi:[1,0]
	v_pk_mul_f32 v[94:95], v[94:95], v[104:105]
	v_mul_f32_e32 v92, 0xbfb8aa3b, v86
	v_pk_mul_f32 v[88:89], v[86:87], v[88:89]
	v_mul_f32_e32 v86, 0xbfb8aa3b, v87
	v_exp_f32_e32 v92, v92
	v_exp_f32_e32 v86, v86
	v_pk_mul_f32 v[96:97], v[96:97], v[100:101]
	v_add_f32_e32 v92, 1.0, v92
	v_add_f32_e32 v86, 1.0, v86
	v_rcp_f32_e32 v92, v92
	v_rcp_f32_e32 v93, v86
	v_cvt_pk_bf16_f32 v86, v94, v95
	v_cvt_pk_bf16_f32 v87, v96, v97
	v_pk_mul_f32 v[92:93], v[88:89], v[92:93]
	v_cvt_pk_bf16_f32 v88, v90, v91
	v_or_b32_e32 v90, 32, v158
	v_mad_i64_i32 v[90:91], s[8:9], v90, s43, v[118:119]
	v_cvt_pk_bf16_f32 v89, v92, v93
	v_lshl_add_u64 v[90:91], v[90:91], 0, v[120:121]
	global_store_dwordx4 v[90:91], v[86:89], off
	s_nop 1
	v_mov_b32_e32 v86, v103
	v_pk_mul_f32 v[82:83], v[82:83], v[86:87] op_sel_hi:[1,0]
	s_nop 0
	v_mul_f32_e32 v87, 0xbfb8aa3b, v82
	v_exp_f32_e32 v87, v87
	s_nop 0
	v_add_f32_e32 v87, 1.0, v87
	v_pk_mul_f32 v[78:79], v[78:79], v[86:87] op_sel_hi:[1,0]
	v_pk_mul_f32 v[80:81], v[80:81], v[86:87] op_sel_hi:[1,0]
	v_pk_mul_f32 v[78:79], v[82:83], v[78:79]
	v_mul_f32_e32 v82, 0xbfb8aa3b, v83
	v_exp_f32_e32 v82, v82
	v_pk_mul_f32 v[74:75], v[74:75], v[86:87] op_sel_hi:[1,0]
	v_pk_mul_f32 v[70:71], v[70:71], v[86:87] op_sel_hi:[1,0]
	v_pk_mul_f32 v[72:73], v[72:73], v[86:87] op_sel_hi:[1,0]
	v_add_f32_e32 v82, 1.0, v82
	v_rcp_f32_e32 v89, v82
	v_pk_mul_f32 v[82:83], v[84:85], v[86:87] op_sel_hi:[1,0]
	v_pk_mul_f32 v[70:71], v[74:75], v[70:71]
	v_mul_f32_e32 v84, 0xbfb8aa3b, v82
	v_pk_mul_f32 v[80:81], v[82:83], v[80:81]
	v_mul_f32_e32 v82, 0xbfb8aa3b, v83
	v_exp_f32_e32 v82, v82
	v_exp_f32_e32 v84, v84
	v_rcp_f32_e32 v88, v87
	v_add_f32_e32 v82, 1.0, v82
	v_rcp_f32_e32 v85, v82
	v_mul_f32_e32 v82, 0xbfb8aa3b, v74
	v_mul_f32_e32 v74, 0xbfb8aa3b, v75
	v_exp_f32_e32 v82, v82
	v_exp_f32_e32 v74, v74
	v_add_f32_e32 v84, 1.0, v84
	v_rcp_f32_e32 v84, v84
	v_add_f32_e32 v82, 1.0, v82
	v_add_f32_e32 v74, 1.0, v74
	v_rcp_f32_e32 v82, v82
	v_rcp_f32_e32 v83, v74
	v_pk_mul_f32 v[78:79], v[78:79], v[88:89]
	v_pk_mul_f32 v[80:81], v[80:81], v[84:85]
	v_pk_mul_f32 v[74:75], v[70:71], v[82:83]
	v_pk_mul_f32 v[70:71], v[76:77], v[86:87] op_sel_hi:[1,0]
	s_nop 0
	v_mul_f32_e32 v76, 0xbfb8aa3b, v70
	v_pk_mul_f32 v[72:73], v[70:71], v[72:73]
	v_mul_f32_e32 v70, 0xbfb8aa3b, v71
	v_exp_f32_e32 v76, v76
	v_exp_f32_e32 v70, v70
	v_cvt_pk_bf16_f32 v71, v80, v81
	v_add_f32_e32 v76, 1.0, v76
	v_add_f32_e32 v70, 1.0, v70
	v_rcp_f32_e32 v76, v76
	v_rcp_f32_e32 v77, v70
	v_cvt_pk_bf16_f32 v70, v78, v79
	v_pk_mul_f32 v[76:77], v[72:73], v[76:77]
	v_cvt_pk_bf16_f32 v72, v74, v75
	v_or_b32_e32 v74, 48, v158
	v_mad_i64_i32 v[74:75], s[8:9], v74, s43, v[118:119]
	v_cvt_pk_bf16_f32 v73, v76, v77
	v_lshl_add_u64 v[74:75], v[74:75], 0, v[120:121]
	global_store_dwordx4 v[74:75], v[70:73], off
	ds_read2_b32 v[70:71], v159 offset0:128 offset1:144
	v_add_u32_e32 v74, 0x80, v158
	s_waitcnt lgkmcnt(0)
; DI unsigned pack2(float lo, float hi) { f32x2_t v = {lo, hi}; return __builtin_bit_cast(unsigned, __builtin_convertvector(v, bf16x2_t)); }
; #define PG8_LAS __attribute__((address_space(3)))
;   DI void operator()(const f32x4 (&acc)[2][2][4][2], const Unit& u, int wr, int wc, int fr, int fq, const PG8_LAS float* rt) const {
;     const int row0 = u.pm * BM + wr * 64 + fr, col0 = u.pn * HALF + wc * 32 + 8 * fq;
; #pragma unroll
;     for (int ai = 0; ai < 2; ++ai)
; #pragma unroll
;       for (int m = 0; m < 4; ++m) {
;         const float r = rt[ai * HALF + wr * 64 + m * 16 + fr];
;         float a[8];
; #pragma unroll
;         for (int n = 0; n < 2; ++n)
; #pragma unroll
;           for (int j = 0; j < 4; ++j) { const float u1 = acc[ai][0][m][n][j] * r, u3 = acc[ai][1][m][n][j] * r; a[4 * n + j] = u1 * u3 * __builtin_amdgcn_rcpf(1.f + __builtin_amdgcn_exp2f(-LOG2E * u1)); }
;         u32x4 w; w.x = pack2(a[0], a[1]); w.y = pack2(a[2], a[3]); w.z = pack2(a[4], a[5]); w.w = pack2(a[6], a[7]);
;         *(u32x4*)(O + (size_t)(row0 + ai * HALF + m * 16) * DFF + col0) = w; }
	v_pk_mul_f32 v[66:67], v[66:67], v[70:71] op_sel_hi:[1,0]
	v_pk_mul_f32 v[62:63], v[62:63], v[70:71] op_sel_hi:[1,0]
	v_mul_f32_e32 v72, 0xbfb8aa3b, v66
	v_pk_mul_f32 v[62:63], v[66:67], v[62:63]
	v_mul_f32_e32 v66, 0xbfb8aa3b, v67
	v_exp_f32_e32 v66, v66
	v_pk_mul_f32 v[64:65], v[64:65], v[70:71] op_sel_hi:[1,0]
	v_pk_mul_f32 v[58:59], v[58:59], v[70:71] op_sel_hi:[1,0]
	v_pk_mul_f32 v[54:55], v[54:55], v[70:71] op_sel_hi:[1,0]
	v_add_f32_e32 v66, 1.0, v66
	v_rcp_f32_e32 v73, v66
	v_pk_mul_f32 v[66:67], v[68:69], v[70:71] op_sel_hi:[1,0]
	v_pk_mul_f32 v[54:55], v[58:59], v[54:55]
	v_mul_f32_e32 v68, 0xbfb8aa3b, v66
	v_pk_mul_f32 v[64:65], v[66:67], v[64:65]
	v_mul_f32_e32 v66, 0xbfb8aa3b, v67
	v_exp_f32_e32 v66, v66
	v_pk_mul_f32 v[56:57], v[56:57], v[70:71] op_sel_hi:[1,0]
	v_exp_f32_e32 v72, v72
	v_exp_f32_e32 v68, v68
	v_add_f32_e32 v66, 1.0, v66
	v_rcp_f32_e32 v69, v66
	v_mul_f32_e32 v66, 0xbfb8aa3b, v58
	v_mul_f32_e32 v58, 0xbfb8aa3b, v59
	v_exp_f32_e32 v66, v66
	v_exp_f32_e32 v58, v58
	v_add_f32_e32 v72, 1.0, v72
	v_add_f32_e32 v68, 1.0, v68
	v_add_f32_e32 v66, 1.0, v66
	v_add_f32_e32 v58, 1.0, v58
	v_rcp_f32_e32 v66, v66
	v_rcp_f32_e32 v67, v58
	v_rcp_f32_e32 v72, v72
	v_rcp_f32_e32 v68, v68
	v_pk_mul_f32 v[58:59], v[54:55], v[66:67]
	v_pk_mul_f32 v[54:55], v[60:61], v[70:71] op_sel_hi:[1,0]
	v_pk_mul_f32 v[62:63], v[62:63], v[72:73]
	v_mul_f32_e32 v60, 0xbfb8aa3b, v54
	v_pk_mul_f32 v[56:57], v[54:55], v[56:57]
	v_mul_f32_e32 v54, 0xbfb8aa3b, v55
	v_exp_f32_e32 v60, v60
	v_exp_f32_e32 v54, v54
	v_pk_mul_f32 v[64:65], v[64:65], v[68:69]
	v_add_f32_e32 v60, 1.0, v60
	v_add_f32_e32 v54, 1.0, v54
	v_rcp_f32_e32 v60, v60
	v_rcp_f32_e32 v61, v54
	v_cvt_pk_bf16_f32 v54, v62, v63
	v_cvt_pk_bf16_f32 v55, v64, v65
	v_pk_mul_f32 v[60:61], v[56:57], v[60:61]
	v_cvt_pk_bf16_f32 v56, v58, v59
	v_mad_i64_i32 v[58:59], s[8:9], v74, s43, v[118:119]
	v_cvt_pk_bf16_f32 v57, v60, v61
	v_lshl_add_u64 v[58:59], v[58:59], 0, v[120:121]
	global_store_dwordx4 v[58:59], v[54:57], off
	s_nop 1
	v_mov_b32_e32 v54, v71
	v_pk_mul_f32 v[46:47], v[46:47], v[54:55] op_sel_hi:[1,0]
	s_nop 0
	v_mul_f32_e32 v55, 0xbfb8aa3b, v46
	v_exp_f32_e32 v55, v55
	s_nop 0
	v_add_f32_e32 v55, 1.0, v55
	v_pk_mul_f32 v[42:43], v[42:43], v[54:55] op_sel_hi:[1,0]
	v_pk_mul_f32 v[44:45], v[44:45], v[54:55] op_sel_hi:[1,0]
	v_pk_mul_f32 v[42:43], v[46:47], v[42:43]
	v_mul_f32_e32 v46, 0xbfb8aa3b, v47
	v_exp_f32_e32 v46, v46
	v_pk_mul_f32 v[38:39], v[38:39], v[54:55] op_sel_hi:[1,0]
	v_pk_mul_f32 v[34:35], v[34:35], v[54:55] op_sel_hi:[1,0]
	v_pk_mul_f32 v[36:37], v[36:37], v[54:55] op_sel_hi:[1,0]
	v_add_f32_e32 v46, 1.0, v46
	v_rcp_f32_e32 v57, v46
	v_pk_mul_f32 v[46:47], v[48:49], v[54:55] op_sel_hi:[1,0]
	v_pk_mul_f32 v[34:35], v[38:39], v[34:35]
	v_mul_f32_e32 v48, 0xbfb8aa3b, v46
	v_pk_mul_f32 v[44:45], v[46:47], v[44:45]
	v_mul_f32_e32 v46, 0xbfb8aa3b, v47
	v_exp_f32_e32 v46, v46
	v_exp_f32_e32 v48, v48
	v_rcp_f32_e32 v56, v55
	v_add_f32_e32 v46, 1.0, v46
	v_rcp_f32_e32 v49, v46
	v_mul_f32_e32 v46, 0xbfb8aa3b, v38
	v_mul_f32_e32 v38, 0xbfb8aa3b, v39
	v_exp_f32_e32 v46, v46
	v_exp_f32_e32 v38, v38
	v_add_f32_e32 v48, 1.0, v48
	v_rcp_f32_e32 v48, v48
	v_add_f32_e32 v46, 1.0, v46
	v_add_f32_e32 v38, 1.0, v38
	v_rcp_f32_e32 v46, v46
	v_rcp_f32_e32 v47, v38
	v_pk_mul_f32 v[42:43], v[42:43], v[56:57]
	v_pk_mul_f32 v[44:45], v[44:45], v[48:49]
	v_pk_mul_f32 v[38:39], v[34:35], v[46:47]
	v_pk_mul_f32 v[34:35], v[40:41], v[54:55] op_sel_hi:[1,0]
	s_nop 0
	v_mul_f32_e32 v40, 0xbfb8aa3b, v34
	v_pk_mul_f32 v[36:37], v[34:35], v[36:37]
	v_mul_f32_e32 v34, 0xbfb8aa3b, v35
	v_exp_f32_e32 v40, v40
	v_exp_f32_e32 v34, v34
	v_cvt_pk_bf16_f32 v35, v44, v45
	v_add_f32_e32 v40, 1.0, v40
	v_add_f32_e32 v34, 1.0, v34
	v_rcp_f32_e32 v40, v40
	v_rcp_f32_e32 v41, v34
	v_cvt_pk_bf16_f32 v34, v42, v43
	v_pk_mul_f32 v[40:41], v[36:37], v[40:41]
	v_cvt_pk_bf16_f32 v36, v38, v39
	v_add_u32_e32 v38, 0x90, v158
	v_mad_i64_i32 v[38:39], s[8:9], v38, s43, v[118:119]
	v_cvt_pk_bf16_f32 v37, v40, v41
	v_lshl_add_u64 v[38:39], v[38:39], 0, v[120:121]
	global_store_dwordx4 v[38:39], v[34:37], off
	ds_read2_b32 v[34:35], v159 offset0:160 offset1:176
	s_waitcnt lgkmcnt(0)
; DI unsigned pack2(float lo, float hi) { f32x2_t v = {lo, hi}; return __builtin_bit_cast(unsigned, __builtin_convertvector(v, bf16x2_t)); }
; #define PG8_LAS __attribute__((address_space(3)))
; #define PG8_RTAB_LOAD(var, unit) do { if constexpr (Epi::NEEDS_R) { var = *(const uint4*)(E.ssq + (size_t)((unit).pm * BM + (tid >> 1)) * 16 + (tid & 1) * 8); } } while (0)
; #define PG8_RTAB_FIN(var, buf) do { if constexpr (Epi::NEEDS_R) { float ss_ = bflo(var.x) + bfhi(var.x) + bflo(var.y) + bfhi(var.y) + bflo(var.z) + bfhi(var.z) + bflo(var.w) + bfhi(var.w); ss_ += __shfl_xor(ss_, 1); \
;     if (!(tid & 1)) ((PG8_LAS float*)(lds + RT_OFF))[(buf) * 256 + (tid >> 1)] = rsqrtf(ss_ * (1.0f / DM) + EPS); } } while (0)
;   DI void operator()(const f32x4 (&acc)[2][2][4][2], const Unit& u, int wr, int wc, int fr, int fq, const PG8_LAS float* rt) const {
;     ...
;           for (int j = 0; j < 4; ++j) { const float u1 = acc[ai][0][m][n][j] * r, u3 = acc[ai][1][m][n][j] * r; a[4 * n + j] = u1 * u3 * __builtin_amdgcn_rcpf(1.f + __builtin_amdgcn_exp2f(-LOG2E * u1)); }
;         u32x4 w; w.x = pack2(a[0], a[1]); w.y = pack2(a[2], a[3]); w.z = pack2(a[4], a[5]); w.w = pack2(a[6], a[7]);
;         *(u32x4*)(O + (size_t)(row0 + ai * HALF + m * 16) * DFF + col0) = w; }
; template <class Epi>
; DI void gemm_phase(const bf16_t* __restrict__ gA, const bf16_t* __restrict__ gBt, int M, int N, int K, const Epi& E, char* lds_generic) {
;     ...
;     uint4 rtn_ = {0u, 0u, 0u, 0u};
;     if (has_next) PG8_RTAB_LOAD(rtn_, nxt);
;     E(acc, cur, wr, wc, fr, fq, (const PG8_LAS float*)(lds + RT_OFF) + (ui & 1) * 256);
;     if (!has_next) break;
;     PG8_RTAB_FIN(rtn_, (ui + 1) & 1);
	v_pk_mul_f32 v[30:31], v[30:31], v[34:35] op_sel_hi:[1,0]
	v_pk_mul_f32 v[26:27], v[26:27], v[34:35] op_sel_hi:[1,0]
	v_mul_f32_e32 v36, 0xbfb8aa3b, v30
	v_pk_mul_f32 v[26:27], v[30:31], v[26:27]
	v_mul_f32_e32 v30, 0xbfb8aa3b, v31
	v_exp_f32_e32 v30, v30
	v_pk_mul_f32 v[28:29], v[28:29], v[34:35] op_sel_hi:[1,0]
	v_pk_mul_f32 v[22:23], v[22:23], v[34:35] op_sel_hi:[1,0]
	v_pk_mul_f32 v[18:19], v[18:19], v[34:35] op_sel_hi:[1,0]
	v_add_f32_e32 v30, 1.0, v30
	v_rcp_f32_e32 v37, v30
	v_pk_mul_f32 v[30:31], v[32:33], v[34:35] op_sel_hi:[1,0]
	v_pk_mul_f32 v[18:19], v[22:23], v[18:19]
	v_mul_f32_e32 v32, 0xbfb8aa3b, v30
	v_pk_mul_f32 v[28:29], v[30:31], v[28:29]
	v_mul_f32_e32 v30, 0xbfb8aa3b, v31
	v_exp_f32_e32 v30, v30
	v_pk_mul_f32 v[20:21], v[20:21], v[34:35] op_sel_hi:[1,0]
	v_exp_f32_e32 v36, v36
	v_exp_f32_e32 v32, v32
	v_add_f32_e32 v30, 1.0, v30
	v_rcp_f32_e32 v33, v30
	v_mul_f32_e32 v30, 0xbfb8aa3b, v22
	v_mul_f32_e32 v22, 0xbfb8aa3b, v23
	v_exp_f32_e32 v30, v30
	v_exp_f32_e32 v22, v22
	v_add_f32_e32 v36, 1.0, v36
	v_add_f32_e32 v32, 1.0, v32
	v_add_f32_e32 v30, 1.0, v30
	v_add_f32_e32 v22, 1.0, v22
	v_rcp_f32_e32 v30, v30
	v_rcp_f32_e32 v31, v22
	v_rcp_f32_e32 v36, v36
	v_rcp_f32_e32 v32, v32
	v_pk_mul_f32 v[22:23], v[18:19], v[30:31]
	v_pk_mul_f32 v[18:19], v[24:25], v[34:35] op_sel_hi:[1,0]
	v_pk_mul_f32 v[26:27], v[26:27], v[36:37]
	v_mul_f32_e32 v24, 0xbfb8aa3b, v18
	v_pk_mul_f32 v[20:21], v[18:19], v[20:21]
	v_mul_f32_e32 v18, 0xbfb8aa3b, v19
	v_exp_f32_e32 v24, v24
	v_exp_f32_e32 v18, v18
	v_pk_mul_f32 v[28:29], v[28:29], v[32:33]
	v_add_f32_e32 v24, 1.0, v24
	v_add_f32_e32 v18, 1.0, v18
	v_rcp_f32_e32 v24, v24
	v_rcp_f32_e32 v25, v18
	v_cvt_pk_bf16_f32 v18, v26, v27
	v_cvt_pk_bf16_f32 v19, v28, v29
	v_pk_mul_f32 v[24:25], v[20:21], v[24:25]
	v_cvt_pk_bf16_f32 v20, v22, v23
	v_add_u32_e32 v22, 0xa0, v158
	v_mad_i64_i32 v[22:23], s[8:9], v22, s43, v[118:119]
	v_cvt_pk_bf16_f32 v21, v24, v25
	v_lshl_add_u64 v[22:23], v[22:23], 0, v[120:121]
	global_store_dwordx4 v[22:23], v[18:21], off
	s_nop 1
	v_mov_b32_e32 v18, v35
	v_pk_mul_f32 v[14:15], v[14:15], v[18:19] op_sel_hi:[1,0]
	s_nop 0
	v_mul_f32_e32 v19, 0xbfb8aa3b, v14
	v_exp_f32_e32 v19, v19
	s_nop 0
	v_add_f32_e32 v19, 1.0, v19
	v_pk_mul_f32 v[10:11], v[10:11], v[18:19] op_sel_hi:[1,0]
	v_pk_mul_f32 v[12:13], v[12:13], v[18:19] op_sel_hi:[1,0]
	v_pk_mul_f32 v[10:11], v[14:15], v[10:11]
	v_mul_f32_e32 v14, 0xbfb8aa3b, v15
	v_exp_f32_e32 v14, v14
	v_pk_mul_f32 v[6:7], v[6:7], v[18:19] op_sel_hi:[1,0]
	v_pk_mul_f32 v[2:3], v[2:3], v[18:19] op_sel_hi:[1,0]
	v_pk_mul_f32 v[4:5], v[4:5], v[18:19] op_sel_hi:[1,0]
	v_add_f32_e32 v14, 1.0, v14
	v_rcp_f32_e32 v21, v14
	v_pk_mul_f32 v[14:15], v[16:17], v[18:19] op_sel_hi:[1,0]
	v_pk_mul_f32 v[2:3], v[6:7], v[2:3]
	v_mul_f32_e32 v16, 0xbfb8aa3b, v14
	v_pk_mul_f32 v[12:13], v[14:15], v[12:13]
	v_mul_f32_e32 v14, 0xbfb8aa3b, v15
	v_exp_f32_e32 v14, v14
	v_exp_f32_e32 v16, v16
	v_rcp_f32_e32 v20, v19
	v_add_f32_e32 v14, 1.0, v14
	v_rcp_f32_e32 v17, v14
	v_mul_f32_e32 v14, 0xbfb8aa3b, v6
	v_mul_f32_e32 v6, 0xbfb8aa3b, v7
	v_exp_f32_e32 v14, v14
	v_exp_f32_e32 v6, v6
	v_add_f32_e32 v16, 1.0, v16
	v_rcp_f32_e32 v16, v16
	v_add_f32_e32 v14, 1.0, v14
	v_add_f32_e32 v6, 1.0, v6
	v_rcp_f32_e32 v14, v14
	v_rcp_f32_e32 v15, v6
	v_pk_mul_f32 v[10:11], v[10:11], v[20:21]
	v_pk_mul_f32 v[12:13], v[12:13], v[16:17]
	v_pk_mul_f32 v[6:7], v[2:3], v[14:15]
	v_pk_mul_f32 v[2:3], v[8:9], v[18:19] op_sel_hi:[1,0]
	s_nop 0
	v_mul_f32_e32 v8, 0xbfb8aa3b, v2
	v_pk_mul_f32 v[4:5], v[2:3], v[4:5]
	v_mul_f32_e32 v2, 0xbfb8aa3b, v3
	v_exp_f32_e32 v8, v8
	v_exp_f32_e32 v2, v2
	v_cvt_pk_bf16_f32 v3, v12, v13
	v_add_f32_e32 v8, 1.0, v8
	v_add_f32_e32 v2, 1.0, v2
	v_rcp_f32_e32 v8, v8
	v_rcp_f32_e32 v9, v2
	v_cvt_pk_bf16_f32 v2, v10, v11
	v_pk_mul_f32 v[8:9], v[4:5], v[8:9]
	v_cvt_pk_bf16_f32 v4, v6, v7
	v_add_u32_e32 v6, 0xb0, v158
	v_mad_i64_i32 v[6:7], s[8:9], v6, s43, v[118:119]
	v_cvt_pk_bf16_f32 v5, v8, v9
	v_lshl_add_u64 v[6:7], v[6:7], 0, v[120:121]
	global_store_dwordx4 v[6:7], v[2:5], off
	s_cbranch_vccnz .LBB0_597
	s_waitcnt vmcnt(8)
	v_lshlrev_b32_e32 v2, 16, v50
	v_and_b32_e32 v3, 0xffff0000, v50
	v_add_f32_e32 v2, v2, v3
	v_lshlrev_b32_e32 v3, 16, v51
	v_add_f32_e32 v2, v2, v3
	v_and_b32_e32 v3, 0xffff0000, v51
	v_add_f32_e32 v2, v2, v3
	v_lshlrev_b32_e32 v3, 16, v52
	v_add_f32_e32 v2, v2, v3
	v_and_b32_e32 v3, 0xffff0000, v52
	v_add_f32_e32 v2, v2, v3
	v_lshlrev_b32_e32 v3, 16, v53
	v_add_f32_e32 v2, v2, v3
	v_and_b32_e32 v3, 0xffff0000, v53
	v_add_f32_e32 v2, v2, v3
	ds_bpermute_b32 v3, v151, v2
	s_and_saveexec_b64 s[8:9], s[36:37]
	s_xor_b64 s[28:29], exec, s[8:9]
	s_cbranch_execz .LBB0_596
	s_waitcnt lgkmcnt(0)
	v_add_f32_e32 v2, v2, v3
	v_fmamk_f32 v2, v2, 0x3a800000, v234
	v_cmp_gt_f32_e32 vcc, s97, v2
	v_mul_f32_e32 v3, 0x4b800000, v2
	s_lshl_b32 s8, s18, 10
	v_cndmask_b32_e32 v2, v2, v3, vcc
	v_rsq_f32_e32 v2, v2
	s_and_b32 s8, s8, 0x400
	v_mul_f32_e32 v3, 0x45800000, v2
	v_cndmask_b32_e32 v2, v2, v3, vcc
	v_add_u32_e32 v3, s8, v152
	ds_write_b32 v3, v2
	s_branch .LBB0_596
